# v7 + start stagger: in the six residual-epilogue GEMM phases half of each XCD's workgroups begin one s_sleep 127 later so the epilogue memory bursts de-phase
# baseline (speedup 1.0000x reference)
.LBB0_11:
	s_mov_b32 s0, 0x14a84
	s_bitcmp1_b32 s0, s82
	s_cbranch_scc0 .Lstg_done
	s_bitcmp1_b32 s28, 3
	s_cbranch_scc0 .Lstg_done
	s_sleep 127
